# NSA tile loops: first V-fragment batch issued right after the QK MFMAs into the dead K-fragment registers (re-test of the earlier variant with paired timing)
# baseline (speedup 1.0000x reference)
.LBB0_2735:
	s_and_b32 s47, s31, 0x2000
	v_add_u32_e32 v112, s47, v142
	ds_read_b128 v[34:37], v112
	ds_read_b128 v[146:149], v112 offset:2048
	ds_read_b128 v[230:233], v112 offset:512
	ds_read_b128 v[234:237], v112 offset:2560
	ds_read_b128 v[238:241], v112 offset:4096
	ds_read_b128 v[242:245], v112 offset:4608
	ds_read_b128 v[246:249], v112 offset:6144
	ds_read_b128 v[250:253], v112 offset:6656
	s_waitcnt lgkmcnt(6)
	v_mfma_f32_32x32x16_bf16 v[50:65], v[34:37], v[66:69], 0
	v_mfma_f32_32x32x16_bf16 v[50:65], v[146:149], v[70:73], v[50:65]
	s_waitcnt lgkmcnt(4)
	v_mfma_f32_32x32x16_bf16 v[34:49], v[230:233], v[66:69], 0
	v_mfma_f32_32x32x16_bf16 v[34:49], v[234:237], v[70:73], v[34:49]
	s_waitcnt lgkmcnt(3)
	v_mfma_f32_32x32x16_bf16 v[50:65], v[238:241], v[74:77], v[50:65]
	s_waitcnt lgkmcnt(2)
	v_mfma_f32_32x32x16_bf16 v[34:49], v[242:245], v[74:77], v[34:49]
	s_waitcnt lgkmcnt(1)
	v_mfma_f32_32x32x16_bf16 v[50:65], v[246:249], v[78:81], v[50:65]
	s_waitcnt lgkmcnt(0)
	v_mfma_f32_32x32x16_bf16 v[34:49], v[250:253], v[78:81], v[34:49]
	v_add_u32_e32 v229, s47, v125
	ds_read_b64_tr_b16 v[230:231],v229 offset:0
	ds_read_b64_tr_b16 v[232:233],v229 offset:512
	ds_read_b64_tr_b16 v[234:235],v229 offset:1024
	ds_read_b64_tr_b16 v[236:237],v229 offset:1536
	ds_read_b64_tr_b16 v[238:239],v229 offset:2048
	ds_read_b64_tr_b16 v[240:241],v229 offset:2560
	ds_read_b64_tr_b16 v[242:243],v229 offset:3072
	ds_read_b64_tr_b16 v[244:245],v229 offset:3584
	v_cvt_f32_i32_e32 v112, v121
	v_cmp_lt_i32_e64 s[22:23], 62, v1
	s_cmp_eq_u64 s[22:23], exec
	v_fma_f32 v154, v90, v112, v141
	v_add_f32_e32 v146, v120, v154
	v_add_f32_e32 v148, v105, v154
	v_add_f32_e32 v147, v92, v146
	v_add_f32_e32 v149, v92, v148
	s_nop 0
	v_pk_add_f32 v[112:113], v[146:147], v[50:51]
	v_pk_add_f32 v[50:51], v[102:103], v[146:147] op_sel_hi:[1,0]
	v_add_f32_e32 v152, v107, v154
	v_pk_add_f32 v[50:51], v[50:51], v[52:53]
	v_pk_add_f32 v[52:53], v[148:149], v[54:55]
	v_pk_add_f32 v[54:55], v[102:103], v[148:149] op_sel_hi:[1,0]
	v_add_f32_e32 v149, v119, v154
	v_pk_add_f32 v[54:55], v[54:55], v[56:57]
	v_add_f32_e32 v56, v120, v149
	v_add_f32_e32 v57, v92, v56
	v_pk_add_f32 v[34:35], v[56:57], v[34:35]
	v_add_f32_e32 v57, v102, v56
	v_add_f32_e32 v146, v57, v36
	v_mov_b32_e32 v57, v149
	v_pk_add_f32 v[150:151], v[104:105], v[56:57]
	v_mov_b32_e32 v36, v37
	v_mov_b32_e32 v37, v38
	v_pk_add_f32 v[56:57], v[92:93], v[150:151] op_sel:[0,1]
	v_mov_b32_e32 v38, v39
	v_mov_b32_e32 v39, v40
	v_add_f32_e32 v153, v92, v152
	v_mov_b32_e32 v148, v151
	v_pk_add_f32 v[36:37], v[150:151], v[36:37]
	v_pk_add_f32 v[38:39], v[56:57], v[38:39]
	v_pk_add_f32 v[56:57], v[152:153], v[58:59]
	v_pk_add_f32 v[58:59], v[102:103], v[152:153] op_sel_hi:[1,0]
	v_pk_add_f32 v[150:151], v[106:107], v[148:149]
	v_add_f32_e32 v152, v109, v154
	v_pk_add_f32 v[58:59], v[58:59], v[60:61]
	v_mov_b32_e32 v40, v41
	v_mov_b32_e32 v41, v42
	v_pk_add_f32 v[60:61], v[92:93], v[150:151] op_sel:[0,1]
	v_mov_b32_e32 v42, v43
	v_mov_b32_e32 v43, v44
	v_add_f32_e32 v153, v92, v152
	v_pk_add_f32 v[42:43], v[60:61], v[42:43]
	v_pk_add_f32 v[60:61], v[152:153], v[62:63]
	v_pk_add_f32 v[62:63], v[102:103], v[152:153] op_sel_hi:[1,0]
	v_mov_b32_e32 v148, v151
	v_pk_add_f32 v[62:63], v[62:63], v[64:65]
	v_pk_add_f32 v[64:65], v[108:109], v[148:149]
	v_mov_b32_e32 v44, v45
	v_mov_b32_e32 v45, v46
	v_pk_add_f32 v[148:149], v[92:93], v[64:65] op_sel:[0,1]
	v_mov_b32_e32 v46, v47
	v_mov_b32_e32 v47, v48
	v_add_f32_e32 v48, v104, v65
	v_pk_add_f32 v[40:41], v[150:151], v[40:41]
	v_pk_add_f32 v[44:45], v[64:65], v[44:45]
	v_pk_add_f32 v[46:47], v[148:149], v[46:47]
	v_add_f32_e32 v64, v48, v49
	s_cbranch_scc1 .LBB0_2737
	v_add_u32_e32 v48, v145, v1
	v_cmp_gt_i32_e64 s[22:23], 0, v48
	s_or_b64 s[22:23], s[6:7], s[22:23]
	v_cmp_gt_i32_e64 s[24:25], 40, v48
	v_cndmask_b32_e64 v112, v112, v132, s[22:23]
	v_cmp_gt_i32_e64 s[22:23], 32, v48
	s_or_b64 s[22:23], s[12:13], s[22:23]
	s_nop 0
	v_cndmask_b32_e64 v34, v34, v132, s[22:23]
	v_cmp_gt_i32_e64 s[22:23], 1, v48
	s_or_b64 s[22:23], s[6:7], s[22:23]
	s_nop 0
	v_cndmask_b32_e64 v113, v113, v132, s[22:23]
	v_cmp_gt_i32_e64 s[22:23], 33, v48
	s_or_b64 s[22:23], s[12:13], s[22:23]
	s_nop 0
	v_cndmask_b32_e64 v35, v35, v132, s[22:23]
	v_cmp_gt_i32_e64 s[22:23], 2, v48
	s_or_b64 s[22:23], s[6:7], s[22:23]
	s_nop 0
	v_cndmask_b32_e64 v50, v50, v132, s[22:23]
	v_cmp_gt_i32_e64 s[22:23], 34, v48
	s_or_b64 s[22:23], s[12:13], s[22:23]
	s_nop 0
	v_cndmask_b32_e64 v146, v146, v132, s[22:23]
	v_cmp_gt_i32_e64 s[22:23], 3, v48
	s_or_b64 s[22:23], s[6:7], s[22:23]
	s_nop 0
	v_cndmask_b32_e64 v51, v51, v132, s[22:23]
	v_cmp_gt_i32_e64 s[22:23], 8, v48
	s_or_b64 s[22:23], s[8:9], s[22:23]
	s_nop 0
	v_cndmask_b32_e64 v52, v52, v132, s[22:23]
	v_cmp_gt_i32_e64 s[22:23], 35, v48
	s_or_b64 s[22:23], s[12:13], s[22:23]
	s_nop 0
	v_cndmask_b32_e64 v36, v36, v132, s[22:23]
	s_or_b64 s[22:23], s[10:11], s[24:25]
	v_cndmask_b32_e64 v37, v37, v132, s[22:23]
	v_cmp_gt_i32_e64 s[22:23], 9, v48
	s_or_b64 s[22:23], s[8:9], s[22:23]
	s_nop 0
	v_cndmask_b32_e64 v53, v53, v132, s[22:23]
	v_cmp_gt_i32_e64 s[22:23], 41, v48
	s_or_b64 s[22:23], s[10:11], s[22:23]
	s_nop 0
	v_cndmask_b32_e64 v38, v38, v132, s[22:23]
	v_cmp_gt_i32_e64 s[22:23], 10, v48
	s_or_b64 s[22:23], s[8:9], s[22:23]
	s_nop 0
	v_cndmask_b32_e64 v54, v54, v132, s[22:23]
	v_cmp_gt_i32_e64 s[22:23], 42, v48
	s_or_b64 s[22:23], s[10:11], s[22:23]
	s_nop 0
	v_cndmask_b32_e64 v39, v39, v132, s[22:23]
	v_cmp_gt_i32_e64 s[22:23], 11, v48
	s_or_b64 s[22:23], s[8:9], s[22:23]
	s_nop 0
	v_cndmask_b32_e64 v55, v55, v132, s[22:23]
	v_cmp_gt_i32_e64 s[22:23], 43, v48
	s_or_b64 s[22:23], s[10:11], s[22:23]
	s_nop 0
	v_cndmask_b32_e64 v40, v40, v132, s[22:23]
	v_cmp_gt_i32_e64 s[22:23], 16, v48
	s_or_b64 s[22:23], s[14:15], s[22:23]
	s_nop 0
	v_cndmask_b32_e64 v56, v56, v132, s[22:23]
	v_cmp_gt_i32_e64 s[22:23], 48, v48
	s_or_b64 s[22:23], s[16:17], s[22:23]
	s_nop 0
	v_cndmask_b32_e64 v41, v41, v132, s[22:23]
	v_cmp_gt_i32_e64 s[22:23], 17, v48
	s_or_b64 s[22:23], s[14:15], s[22:23]
	s_nop 0
	v_cndmask_b32_e64 v57, v57, v132, s[22:23]
	v_cmp_gt_i32_e64 s[22:23], 49, v48
	s_or_b64 s[22:23], s[16:17], s[22:23]
	s_nop 0
	v_cndmask_b32_e64 v42, v42, v132, s[22:23]
	v_cmp_gt_i32_e64 s[22:23], 18, v48
	s_or_b64 s[22:23], s[14:15], s[22:23]
	s_nop 0
	v_cndmask_b32_e64 v58, v58, v132, s[22:23]
	v_cmp_gt_i32_e64 s[22:23], 50, v48
	s_or_b64 s[22:23], s[16:17], s[22:23]
	s_nop 0
	v_cndmask_b32_e64 v43, v43, v132, s[22:23]
	v_cmp_gt_i32_e64 s[22:23], 19, v48
	s_or_b64 s[22:23], s[14:15], s[22:23]
	s_nop 0
	v_cndmask_b32_e64 v59, v59, v132, s[22:23]
	v_cmp_gt_i32_e64 s[22:23], 51, v48
	s_or_b64 s[22:23], s[16:17], s[22:23]
	s_nop 0
	v_cndmask_b32_e64 v44, v44, v132, s[22:23]
	v_cmp_gt_i32_e64 s[22:23], 24, v48
	s_or_b64 s[22:23], s[18:19], s[22:23]
	s_nop 0
	v_cndmask_b32_e64 v60, v60, v132, s[22:23]
	v_cmp_gt_i32_e64 s[22:23], 56, v48
	s_or_b64 s[22:23], s[20:21], s[22:23]
	s_nop 0
	v_cndmask_b32_e64 v45, v45, v132, s[22:23]
	v_cmp_gt_i32_e64 s[22:23], 25, v48
	s_or_b64 s[22:23], s[18:19], s[22:23]
	s_nop 0
	v_cndmask_b32_e64 v61, v61, v132, s[22:23]
	v_cmp_gt_i32_e64 s[22:23], 57, v48
	s_or_b64 s[22:23], s[20:21], s[22:23]
	s_nop 0
	v_cndmask_b32_e64 v46, v46, v132, s[22:23]
	v_cmp_gt_i32_e64 s[22:23], 26, v48
	s_or_b64 s[22:23], s[18:19], s[22:23]
	s_nop 0
	v_cndmask_b32_e64 v62, v62, v132, s[22:23]
	v_cmp_gt_i32_e64 s[22:23], 58, v48
	s_or_b64 s[22:23], s[20:21], s[22:23]
	s_nop 0
	v_cndmask_b32_e64 v47, v47, v132, s[22:23]
	v_cmp_gt_i32_e64 s[22:23], 27, v48
	s_or_b64 s[22:23], s[18:19], s[22:23]
	s_nop 0
	v_cndmask_b32_e64 v63, v63, v132, s[22:23]
	v_cmp_gt_i32_e64 s[22:23], 59, v48
	s_or_b64 s[22:23], s[20:21], s[22:23]
	s_nop 0
	v_cndmask_b32_e64 v64, v64, v132, s[22:23]

.LBB0_2741:
	s_or_b64 exec, exec, s[22:23]
	v_mul_f32_e32 v45, v123, v65
	s_waitcnt lgkmcnt(0)
	v_mul_f32_e32 v46, v123, v112
	v_mul_f32_e32 v47, v123, v113
	v_mul_f32_e32 v60, v123, v147
	v_mul_f32_e32 v56, v123, v56
	v_mul_f32_e32 v57, v123, v57
	v_mul_f32_e32 v58, v123, v58
	v_mul_f32_e32 v59, v123, v59
	v_mul_f32_e32 v61, v123, v62
	v_mul_f32_e32 v62, v123, v63
	v_mul_f32_e32 v63, v123, v146
	v_mul_f32_e32 v64, v123, v148
	v_mul_f32_e32 v65, v123, v149
	v_mul_f32_e32 v112, v123, v42
	v_mul_f32_e32 v113, v123, v43
	v_mul_f32_e32 v146, v123, v44
	v_cvt_pk_bf16_f32 v42, v45, v55
	v_cvt_pk_bf16_f32 v43, v46, v54
	v_cvt_pk_bf16_f32 v44, v47, v53
	v_cvt_pk_bf16_f32 v45, v60, v52
	v_cvt_pk_bf16_f32 v52, v56, v51
	v_cvt_pk_bf16_f32 v53, v57, v50
	v_cvt_pk_bf16_f32 v54, v58, v49
	v_cvt_pk_bf16_f32 v55, v59, v48
	v_cvt_pk_bf16_f32 v46, v61, v41
	v_cvt_pk_bf16_f32 v47, v62, v40
	v_cvt_pk_bf16_f32 v48, v63, v39
	v_cvt_pk_bf16_f32 v49, v64, v38
	v_cvt_pk_bf16_f32 v38, v65, v37
	v_cvt_pk_bf16_f32 v39, v112, v36
	v_cvt_pk_bf16_f32 v40, v113, v35
	v_cvt_pk_bf16_f32 v41, v146, v34
	v_add_u32_e32 v50, s47, v125
	s_waitcnt lgkmcnt(0)
	s_nop 0
	v_mfma_f32_32x32x16_bf16 v[18:33], v[42:45], v[230:233], v[18:33]
	ds_read_b64_tr_b16 v[34:35],v50 offset:4096
	ds_read_b64_tr_b16 v[36:37],v50 offset:4608
	v_mfma_f32_32x32x16_bf16 v[18:33], v[52:55], v[234:237], v[18:33]
	ds_read_b64_tr_b16 v[56:57],v50 offset:5120
	ds_read_b64_tr_b16 v[58:59],v50 offset:5632
	v_mfma_f32_32x32x16_bf16 v[18:33], v[46:49], v[238:241], v[18:33]
	ds_read_b64_tr_b16 v[60:61],v50 offset:6144
	ds_read_b64_tr_b16 v[62:63],v50 offset:6656
	v_mfma_f32_32x32x16_bf16 v[18:33], v[38:41], v[242:245], v[18:33]
	ds_read_b64_tr_b16 v[146:147],v50 offset:7168
	ds_read_b64_tr_b16 v[148:149],v50 offset:7680
	s_waitcnt lgkmcnt(0)
	v_mfma_f32_32x32x16_bf16 v[2:17], v[42:45], v[34:37], v[2:17]
	s_cmp_ge_u32 s46, s30
	v_mfma_f32_32x32x16_bf16 v[2:17], v[52:55], v[56:59], v[2:17]
	v_mfma_f32_32x32x16_bf16 v[2:17], v[46:49], v[60:63], v[2:17]
	v_mfma_f32_32x32x16_bf16 v[2:17], v[38:41], v[146:149], v[2:17]
	s_cbranch_scc1 .LBB0_2743
	s_xor_b32 s22, s47, 0x2000
	v_add_u32_e32 v34, s22, v124
	s_waitcnt vmcnt(0)
	ds_write_b128 v34, v[82:85]
	ds_write_b128 v34, v[86:89] offset:16384

.LBB0_2814:
	s_add_i32 s26, s28, -8
	v_mov_b32_e32 v34, s26
	ds_read_b32 v116, v34
	s_and_b32 s74, s79, 1
	s_waitcnt lgkmcnt(0)
	v_ashrrev_i32_e32 v34, 5, v116
	v_lshl_add_u32 v98, v34, 2, v165
	ds_read_b32 v34, v98
	v_lshlrev_b32_e64 v109, v116, 1
	s_waitcnt lgkmcnt(0)
	v_and_b32_e32 v34, v109, v34
	v_cmp_ne_u32_e32 vcc, 0, v34
	s_cbranch_vccz .LBB0_2823
	s_lshl_b32 s76, s74, 13
	v_add_u32_e32 v117, s76, v167
	ds_read_b128 v[34:37], v117
	ds_read_b128 v[118:121], v117 offset:2048
	ds_read_b128 v[230:233], v117 offset:512
	ds_read_b128 v[234:237], v117 offset:2560
	ds_read_b128 v[238:241], v117 offset:4096
	ds_read_b128 v[242:245], v117 offset:4608
	ds_read_b128 v[246:249], v117 offset:6144
	ds_read_b128 v[250:253], v117 offset:6656
	s_waitcnt lgkmcnt(6)
	v_mfma_f32_32x32x16_bf16 v[50:65], v[34:37], v[66:69], 0
	v_mfma_f32_32x32x16_bf16 v[50:65], v[118:121], v[70:73], v[50:65]
	s_waitcnt lgkmcnt(4)
	v_mfma_f32_32x32x16_bf16 v[34:49], v[230:233], v[66:69], 0
	v_mfma_f32_32x32x16_bf16 v[34:49], v[234:237], v[70:73], v[34:49]
	s_waitcnt lgkmcnt(3)
	v_mfma_f32_32x32x16_bf16 v[50:65], v[238:241], v[74:77], v[50:65]
	s_waitcnt lgkmcnt(2)
	v_mfma_f32_32x32x16_bf16 v[34:49], v[242:245], v[74:77], v[34:49]
	s_waitcnt lgkmcnt(1)
	v_mfma_f32_32x32x16_bf16 v[50:65], v[246:249], v[78:81], v[50:65]
	s_waitcnt lgkmcnt(0)
	v_mfma_f32_32x32x16_bf16 v[34:49], v[250:253], v[78:81], v[34:49]
	v_add_u32_e32 v229, s76, v163
	ds_read_b64_tr_b16 v[230:231],v229 offset:0
	ds_read_b64_tr_b16 v[232:233],v229 offset:512
	ds_read_b64_tr_b16 v[234:235],v229 offset:1024
	ds_read_b64_tr_b16 v[236:237],v229 offset:1536
	ds_read_b64_tr_b16 v[238:239],v229 offset:2048
	ds_read_b64_tr_b16 v[240:241],v229 offset:2560
	ds_read_b64_tr_b16 v[242:243],v229 offset:3072
	ds_read_b64_tr_b16 v[244:245],v229 offset:3584
	v_lshlrev_b32_e32 v116, 6, v116
	ds_read_b32 v117, v98
	v_sub_u32_e32 v98, v116, v96
	v_cvt_f32_i32_e32 v118, v98
	v_sub_u32_e32 v98, v96, v116
	v_cmp_lt_i32_e32 vcc, 62, v98
	s_waitcnt lgkmcnt(0)
	v_and_b32_e32 v109, v117, v109
	v_fma_f32 v116, v90, v118, v164
	v_sub_f32_e32 v171, v116, v168
	v_add_f32_e32 v116, v144, v171
	v_add_f32_e32 v117, v90, v116
	v_pk_add_f32 v[118:119], v[116:117], v[50:51]
	v_pk_add_f32 v[50:51], v[114:115], v[116:117] op_sel_hi:[1,0]
	v_add_f32_e32 v173, v143, v171
	v_pk_add_f32 v[116:117], v[50:51], v[52:53]
	v_add_f32_e32 v50, v111, v171
	v_add_f32_e32 v51, v90, v50
	v_add_f32_e32 v120, v144, v173
	v_pk_add_f32 v[52:53], v[50:51], v[54:55]
	v_pk_add_f32 v[50:51], v[114:115], v[50:51] op_sel_hi:[1,0]
	v_add_f32_e32 v121, v90, v120
	v_pk_add_f32 v[50:51], v[50:51], v[56:57]
	v_pk_add_f32 v[56:57], v[120:121], v[34:35]
	v_add_f32_e32 v34, v91, v120
	v_mov_b32_e32 v121, v173
	v_add_f32_e32 v54, v34, v36
	v_pk_add_f32 v[122:123], v[110:111], v[120:121]
	v_mov_b32_e32 v34, v37
	v_mov_b32_e32 v35, v38
	v_pk_add_f32 v[124:125], v[122:123], v[34:35]
	v_pk_add_f32 v[34:35], v[90:91], v[122:123] op_sel:[0,1]
	v_mov_b32_e32 v36, v39
	v_mov_b32_e32 v37, v40
	v_pk_add_f32 v[120:121], v[34:35], v[36:37]
	v_add_f32_e32 v34, v92, v171
	v_add_f32_e32 v35, v90, v34
	v_pk_add_f32 v[38:39], v[34:35], v[58:59]
	v_pk_add_f32 v[34:35], v[114:115], v[34:35] op_sel_hi:[1,0]
	v_mov_b32_e32 v172, v123
	v_pk_add_f32 v[34:35], v[34:35], v[60:61]
	v_pk_add_f32 v[60:61], v[112:113], v[172:173]
	v_mov_b32_e32 v36, v41
	v_mov_b32_e32 v37, v42
	v_pk_add_f32 v[122:123], v[60:61], v[36:37]
	v_pk_add_f32 v[36:37], v[90:91], v[60:61] op_sel:[0,1]
	v_mov_b32_e32 v40, v43
	v_mov_b32_e32 v41, v44
	v_mov_b32_e32 v172, v61
	v_cmp_ne_u32_e64 s[26:27], 0, v109
	v_pk_add_f32 v[58:59], v[36:37], v[40:41]
	v_add_f32_e32 v36, v103, v171
	v_pk_add_f32 v[42:43], v[102:103], v[172:173]
	v_mov_b32_e32 v44, v45
	v_mov_b32_e32 v45, v46
	s_and_b64 vcc, s[26:27], vcc
	v_add_f32_e32 v37, v90, v36
	v_pk_add_f32 v[60:61], v[42:43], v[44:45]
	v_pk_add_f32 v[44:45], v[90:91], v[42:43] op_sel:[0,1]
	v_add_f32_e32 v42, v110, v43
	v_pk_add_f32 v[40:41], v[36:37], v[62:63]
	v_pk_add_f32 v[36:37], v[114:115], v[36:37] op_sel_hi:[1,0]
	v_mov_b32_e32 v46, v47
	v_mov_b32_e32 v47, v48
	v_pk_add_f32 v[36:37], v[36:37], v[64:65]
	v_pk_add_f32 v[62:63], v[44:45], v[46:47]
	s_cmp_eq_u64 vcc, exec
	v_add_f32_e32 v43, v42, v49
	s_cbranch_scc1 .LBB0_2817
	v_sub_u32_e32 v42, v98, v162
	v_cndmask_b32_e64 v64, v134, v42, s[26:27]
	v_cmp_gt_i32_e32 vcc, 0, v64
	s_or_b64 vcc, s[10:11], vcc
	v_cmp_gt_i32_e64 s[26:27], 40, v64
	v_cndmask_b32_e32 v118, v118, v132, vcc
	v_cmp_gt_i32_e32 vcc, 32, v64
	s_or_b64 vcc, s[16:17], vcc
	s_nop 0
	v_cndmask_b32_e32 v56, v56, v132, vcc
	v_cmp_gt_i32_e32 vcc, 1, v64
	s_or_b64 vcc, s[10:11], vcc
	s_nop 0
	v_cndmask_b32_e32 v119, v119, v132, vcc
	v_cmp_gt_i32_e32 vcc, 33, v64
	s_or_b64 vcc, s[16:17], vcc
	s_nop 0
	v_cndmask_b32_e32 v57, v57, v132, vcc
	v_cmp_gt_i32_e32 vcc, 2, v64
	s_or_b64 vcc, s[10:11], vcc
	s_nop 0
	v_cndmask_b32_e32 v116, v116, v132, vcc
	v_cmp_gt_i32_e32 vcc, 34, v64
	s_or_b64 vcc, s[16:17], vcc
	s_nop 0
	v_cndmask_b32_e32 v54, v54, v132, vcc
	v_cmp_gt_i32_e32 vcc, 3, v64
	s_or_b64 vcc, s[10:11], vcc
	s_nop 0
	v_cndmask_b32_e32 v117, v117, v132, vcc
	v_cmp_gt_i32_e32 vcc, 8, v64
	s_or_b64 vcc, s[12:13], vcc
	s_nop 0
	v_cndmask_b32_e32 v52, v52, v132, vcc
	v_cmp_gt_i32_e32 vcc, 35, v64
	s_or_b64 vcc, s[16:17], vcc
	s_nop 0
	v_cndmask_b32_e32 v55, v124, v132, vcc
	s_or_b64 vcc, s[14:15], s[26:27]
	v_cndmask_b32_e32 v44, v125, v132, vcc
	v_cmp_gt_i32_e32 vcc, 9, v64
	s_or_b64 vcc, s[12:13], vcc
	s_nop 0
	v_cndmask_b32_e32 v53, v53, v132, vcc
	v_cmp_gt_i32_e32 vcc, 41, v64
	s_or_b64 vcc, s[14:15], vcc
	s_nop 0
	v_cndmask_b32_e32 v45, v120, v132, vcc
	v_cmp_gt_i32_e32 vcc, 10, v64
	s_or_b64 vcc, s[12:13], vcc
	s_nop 0
	v_cndmask_b32_e32 v50, v50, v132, vcc
	v_cmp_gt_i32_e32 vcc, 42, v64
	s_or_b64 vcc, s[14:15], vcc
	s_nop 0
	v_cndmask_b32_e32 v46, v121, v132, vcc
	v_cmp_gt_i32_e32 vcc, 11, v64
	s_or_b64 vcc, s[12:13], vcc
	s_nop 0
	v_cndmask_b32_e32 v51, v51, v132, vcc
	v_cmp_gt_i32_e32 vcc, 43, v64
	s_or_b64 vcc, s[14:15], vcc
	s_nop 0
	v_cndmask_b32_e32 v47, v122, v132, vcc
	v_cmp_gt_i32_e32 vcc, 16, v64
	s_or_b64 vcc, s[18:19], vcc
	s_nop 0
	v_cndmask_b32_e32 v38, v38, v132, vcc
	v_cmp_gt_i32_e32 vcc, 48, v64
	s_or_b64 vcc, s[20:21], vcc
	s_nop 0
	v_cndmask_b32_e32 v48, v123, v132, vcc
	v_cmp_gt_i32_e32 vcc, 17, v64
	s_or_b64 vcc, s[18:19], vcc
	s_nop 0
	v_cndmask_b32_e32 v39, v39, v132, vcc
	v_cmp_gt_i32_e32 vcc, 49, v64
	s_or_b64 vcc, s[20:21], vcc
	s_nop 0
	v_cndmask_b32_e32 v49, v58, v132, vcc
	v_cmp_gt_i32_e32 vcc, 18, v64
	s_or_b64 vcc, s[18:19], vcc
	s_nop 0
	v_cndmask_b32_e32 v34, v34, v132, vcc
	v_cmp_gt_i32_e32 vcc, 50, v64
	s_or_b64 vcc, s[20:21], vcc
	s_nop 0
	v_cndmask_b32_e32 v58, v59, v132, vcc
	v_cmp_gt_i32_e32 vcc, 19, v64
	s_or_b64 vcc, s[18:19], vcc
	s_nop 0
	v_cndmask_b32_e32 v35, v35, v132, vcc
	v_cmp_gt_i32_e32 vcc, 51, v64
	s_or_b64 vcc, s[20:21], vcc
	s_nop 0
	v_cndmask_b32_e32 v59, v60, v132, vcc
	v_cmp_gt_i32_e32 vcc, 24, v64
	s_or_b64 vcc, s[22:23], vcc
	s_nop 0
	v_cndmask_b32_e32 v40, v40, v132, vcc
	v_cmp_gt_i32_e32 vcc, 56, v64
	s_or_b64 vcc, s[24:25], vcc
	s_nop 0
	v_cndmask_b32_e32 v60, v61, v132, vcc
	v_cmp_gt_i32_e32 vcc, 25, v64
	s_or_b64 vcc, s[22:23], vcc
	s_nop 0
	v_cndmask_b32_e32 v41, v41, v132, vcc
	v_cmp_gt_i32_e32 vcc, 57, v64
	s_or_b64 vcc, s[24:25], vcc
	s_nop 0
	v_cndmask_b32_e32 v61, v62, v132, vcc
	v_cmp_gt_i32_e32 vcc, 26, v64
	s_or_b64 vcc, s[22:23], vcc
	s_nop 0
	v_cndmask_b32_e32 v36, v36, v132, vcc
	v_cmp_gt_i32_e32 vcc, 58, v64
	s_or_b64 vcc, s[24:25], vcc
	s_nop 0
	v_cndmask_b32_e32 v42, v63, v132, vcc
	v_cmp_gt_i32_e32 vcc, 27, v64
	s_or_b64 vcc, s[22:23], vcc
	s_nop 0
	v_cndmask_b32_e32 v37, v37, v132, vcc
	v_cmp_gt_i32_e32 vcc, 59, v64
	s_or_b64 vcc, s[24:25], vcc
	s_nop 0
	v_cndmask_b32_e32 v43, v43, v132, vcc
	s_branch .LBB0_2818

.LBB0_2822:
	v_exp_f32_e32 v109, v118
	v_exp_f32_e32 v124, v56
	v_exp_f32_e32 v98, v119
	v_exp_f32_e32 v56, v57
	v_exp_f32_e32 v125, v54
	v_add_f32_e32 v57, v109, v124
	v_exp_f32_e32 v54, v55
	v_pk_add_f32 v[62:63], v[56:57], v[98:99]
	v_exp_f32_e32 v57, v116
	v_pk_add_f32 v[62:63], v[62:63], v[62:63] op_sel_hi:[0,1]
	v_exp_f32_e32 v62, v117
	v_exp_f32_e32 v40, v40
	v_add_f32_e32 v55, v125, v57
	v_exp_f32_e32 v122, v43
	v_pk_add_f32 v[64:65], v[54:55], v[62:63]
	v_exp_f32_e32 v55, v52
	v_pk_add_f32 v[64:65], v[64:65], v[64:65] op_sel_hi:[0,1]
	v_exp_f32_e32 v63, v44
	v_exp_f32_e32 v64, v53
	v_exp_f32_e32 v44, v45
	v_add_f32_e32 v45, v63, v55
	v_pk_add_f32 v[52:53], v[44:45], v[64:65]
	s_nop 0
	v_pk_add_f32 v[52:53], v[52:53], v[52:53] op_sel_hi:[0,1]
	v_exp_f32_e32 v45, v50
	v_exp_f32_e32 v65, v46
	v_exp_f32_e32 v52, v51
	v_exp_f32_e32 v46, v47
	v_add_f32_e32 v47, v65, v45
	v_pk_add_f32 v[50:51], v[46:47], v[52:53]
	s_nop 0
	v_pk_add_f32 v[50:51], v[50:51], v[50:51] op_sel_hi:[0,1]
	v_exp_f32_e32 v47, v38
	v_exp_f32_e32 v53, v48
	v_exp_f32_e32 v50, v39
	v_exp_f32_e32 v48, v49
	v_add_f32_e32 v49, v53, v47
	v_pk_add_f32 v[38:39], v[48:49], v[50:51]
	s_nop 0
	v_pk_add_f32 v[116:117], v[38:39], v[38:39] op_sel_hi:[0,1]
	v_exp_f32_e32 v39, v34
	v_exp_f32_e32 v49, v58
	v_exp_f32_e32 v116, v35
	v_exp_f32_e32 v58, v59
	v_exp_f32_e32 v51, v60
	v_add_f32_e32 v59, v49, v39
	v_exp_f32_e32 v60, v61
	v_pk_add_f32 v[34:35], v[58:59], v[116:117]
	v_add_f32_e32 v61, v51, v40
	v_pk_add_f32 v[118:119], v[34:35], v[34:35] op_sel_hi:[0,1]
	v_exp_f32_e32 v118, v41
	v_exp_f32_e32 v41, v36
	v_exp_f32_e32 v59, v42
	v_pk_add_f32 v[34:35], v[60:61], v[118:119]
	s_nop 0
	v_pk_add_f32 v[120:121], v[34:35], v[34:35] op_sel_hi:[0,1]
	v_exp_f32_e32 v120, v37
	v_add_f32_e32 v123, v59, v41
	v_pk_add_f32 v[34:35], v[122:123], v[120:121]
	s_nop 0
	v_add_f32_e32 v34, v34, v35
	v_add_f32_e32 v160, v160, v34
	v_cvt_pk_bf16_f32 v34, v109, v98
	v_cvt_pk_bf16_f32 v35, v57, v62
	v_cvt_pk_bf16_f32 v36, v55, v64
	v_cvt_pk_bf16_f32 v37, v45, v52
	v_cvt_pk_bf16_f32 v38, v47, v50
	v_cvt_pk_bf16_f32 v39, v39, v116
	v_cvt_pk_bf16_f32 v40, v40, v118
	v_cvt_pk_bf16_f32 v41, v41, v120
	v_cvt_pk_bf16_f32 v42, v124, v56
	v_cvt_pk_bf16_f32 v43, v125, v54
	v_cvt_pk_bf16_f32 v44, v63, v44
	v_cvt_pk_bf16_f32 v45, v65, v46
	v_cvt_pk_bf16_f32 v46, v53, v48
	v_cvt_pk_bf16_f32 v47, v49, v58
	v_cvt_pk_bf16_f32 v48, v51, v60
	v_cvt_pk_bf16_f32 v49, v59, v122
	v_add_u32_e32 v98, s76, v163
	s_waitcnt lgkmcnt(0)
	s_nop 0
	v_mfma_f32_32x32x16_bf16 v[18:33], v[34:37], v[230:233], v[18:33]
	ds_read_b64_tr_b16 v[50:51],v98 offset:4096
	ds_read_b64_tr_b16 v[52:53],v98 offset:4608
	v_mfma_f32_32x32x16_bf16 v[18:33], v[38:41], v[234:237], v[18:33]
	ds_read_b64_tr_b16 v[54:55],v98 offset:5120
	ds_read_b64_tr_b16 v[56:57],v98 offset:5632
	v_mfma_f32_32x32x16_bf16 v[18:33], v[42:45], v[238:241], v[18:33]
	ds_read_b64_tr_b16 v[58:59],v98 offset:6144
	ds_read_b64_tr_b16 v[60:61],v98 offset:6656
	v_mfma_f32_32x32x16_bf16 v[18:33], v[46:49], v[242:245], v[18:33]
	ds_read_b64_tr_b16 v[62:63],v98 offset:7168
	ds_read_b64_tr_b16 v[64:65],v98 offset:7680
	s_waitcnt lgkmcnt(0)
	v_mfma_f32_32x32x16_bf16 v[2:17], v[34:37], v[50:53], v[2:17]
	v_mfma_f32_32x32x16_bf16 v[2:17], v[38:41], v[54:57], v[2:17]
	v_mfma_f32_32x32x16_bf16 v[2:17], v[42:45], v[58:61], v[2:17]
	v_mfma_f32_32x32x16_bf16 v[2:17], v[46:49], v[62:65], v[2:17]

.LBB0_2878:
	s_and_b32 s18, s15, 0x2000
	v_add_u32_e32 v100, s18, v122
	ds_read_b128 v[34:37], v100
	ds_read_b128 v[150:153], v100 offset:2048
	ds_read_b128 v[230:233], v100 offset:512
	ds_read_b128 v[234:237], v100 offset:2560
	ds_read_b128 v[238:241], v100 offset:4096
	ds_read_b128 v[242:245], v100 offset:4608
	ds_read_b128 v[246:249], v100 offset:6144
	ds_read_b128 v[250:253], v100 offset:6656
	s_waitcnt lgkmcnt(6)
	v_mfma_f32_32x32x16_bf16 v[50:65], v[34:37], v[66:69], 0
	v_mfma_f32_32x32x16_bf16 v[50:65], v[150:153], v[70:73], v[50:65]
	s_waitcnt lgkmcnt(4)
	v_mfma_f32_32x32x16_bf16 v[34:49], v[230:233], v[66:69], 0
	v_mfma_f32_32x32x16_bf16 v[34:49], v[234:237], v[70:73], v[34:49]
	s_waitcnt lgkmcnt(3)
	v_mfma_f32_32x32x16_bf16 v[50:65], v[238:241], v[74:77], v[50:65]
	s_waitcnt lgkmcnt(2)
	v_mfma_f32_32x32x16_bf16 v[34:49], v[242:245], v[74:77], v[34:49]
	s_waitcnt lgkmcnt(1)
	v_mfma_f32_32x32x16_bf16 v[50:65], v[246:249], v[78:81], v[50:65]
	s_waitcnt lgkmcnt(0)
	v_mfma_f32_32x32x16_bf16 v[34:49], v[250:253], v[78:81], v[34:49]
	v_add_u32_e32 v229, s18, v120
	ds_read_b64_tr_b16 v[230:231],v229 offset:0
	ds_read_b64_tr_b16 v[232:233],v229 offset:512
	ds_read_b64_tr_b16 v[234:235],v229 offset:1024
	ds_read_b64_tr_b16 v[236:237],v229 offset:1536
	ds_read_b64_tr_b16 v[238:239],v229 offset:2048
	ds_read_b64_tr_b16 v[240:241],v229 offset:2560
	ds_read_b64_tr_b16 v[242:243],v229 offset:3072
	ds_read_b64_tr_b16 v[244:245],v229 offset:3584
	v_cvt_f32_i32_e32 v100, v148
	v_subrev_u32_e32 v152, 63, v147
	s_movk_i32 s10, 0x1c1
	v_cmp_gt_u32_e32 vcc, s10, v152
	v_fma_f32 v100, v90, v100, v121
	v_sub_f32_e32 v100, v100, v149
	v_add_f32_e32 v150, v144, v100
	v_add_f32_e32 v151, v90, v150
	v_add_f32_e32 v153, v143, v100
	v_pk_add_f32 v[50:51], v[150:151], v[50:51]
	v_pk_add_f32 v[150:151], v[104:105], v[150:151] op_sel_hi:[1,0]
	s_cmp_eq_u64 vcc, exec
	v_pk_add_f32 v[52:53], v[150:151], v[52:53]
	v_add_f32_e32 v150, v144, v153
	v_add_f32_e32 v151, v90, v150
	v_pk_add_f32 v[34:35], v[150:151], v[34:35]
	v_pk_add_f32 v[150:151], v[104:105], v[150:151] op_sel_hi:[1,0]
	s_nop 0
	v_pk_add_f32 v[36:37], v[150:151], v[36:37]
	v_add_f32_e32 v150, v125, v100
	v_add_f32_e32 v151, v90, v150
	v_pk_add_f32 v[54:55], v[150:151], v[54:55]
	v_pk_add_f32 v[150:151], v[104:105], v[150:151] op_sel_hi:[1,0]
	s_nop 0
	v_pk_add_f32 v[56:57], v[150:151], v[56:57]
	v_add_f32_e32 v150, v125, v153
	v_add_f32_e32 v151, v90, v150
	v_pk_add_f32 v[38:39], v[150:151], v[38:39]
	v_pk_add_f32 v[150:151], v[104:105], v[150:151] op_sel_hi:[1,0]
	s_nop 0
	v_pk_add_f32 v[40:41], v[150:151], v[40:41]
	v_add_f32_e32 v150, v92, v100
	v_add_f32_e32 v151, v90, v150
	v_pk_add_f32 v[58:59], v[150:151], v[58:59]
	v_pk_add_f32 v[150:151], v[104:105], v[150:151] op_sel_hi:[1,0]
	s_nop 0
	v_pk_add_f32 v[60:61], v[150:151], v[60:61]
	v_add_f32_e32 v150, v92, v153
	v_add_f32_e32 v151, v90, v150
	v_pk_add_f32 v[42:43], v[150:151], v[42:43]
	v_pk_add_f32 v[150:151], v[104:105], v[150:151] op_sel_hi:[1,0]
	s_nop 0
	v_pk_add_f32 v[44:45], v[150:151], v[44:45]
	v_add_f32_e32 v150, v103, v100
	v_add_f32_e32 v151, v90, v150
	v_pk_add_f32 v[62:63], v[150:151], v[62:63]
	v_pk_add_f32 v[150:151], v[104:105], v[150:151] op_sel_hi:[1,0]
	s_nop 0
	v_pk_add_f32 v[64:65], v[150:151], v[64:65]
	v_add_f32_e32 v150, v103, v153
	v_add_f32_e32 v151, v90, v150
	v_pk_add_f32 v[46:47], v[150:151], v[46:47]
	v_pk_add_f32 v[150:151], v[104:105], v[150:151] op_sel_hi:[1,0]
	s_nop 0
	v_pk_add_f32 v[48:49], v[150:151], v[48:49]
	s_cbranch_scc1 .LBB0_2880
	v_add_u32_e32 v100, v146, v147
	s_movk_i32 s10, 0x200
	v_add_u32_e32 v150, 0xfffffdff, v100
	v_cmp_gt_u32_e32 vcc, s10, v100
	v_add_u32_e32 v151, 0xfffffdfe, v100
	v_add_u32_e32 v152, 0xfffffdc7, v100
	v_cndmask_b32_e32 v50, v132, v50, vcc
	v_cmp_lt_u32_e32 vcc, s34, v150
	v_add_u32_e32 v150, 0xfffffdfd, v100
	v_add_u32_e32 v153, 0xfffffdc8, v100
	v_cndmask_b32_e32 v51, v132, v51, vcc
	v_cmp_lt_u32_e32 vcc, s34, v151
	v_add_u32_e32 v151, 0xfffffdf8, v100
	v_add_u32_e32 v154, 0xfffffdcd, v100
	v_cndmask_b32_e32 v52, v132, v52, vcc
	v_cmp_lt_u32_e32 vcc, s34, v150
	v_add_u32_e32 v150, 0xfffffdf7, v100
	v_add_u32_e32 v155, 0xfffffdce, v100
	v_cndmask_b32_e32 v53, v132, v53, vcc
	v_cmp_lt_u32_e32 vcc, s34, v151
	v_add_u32_e32 v151, 0xfffffdf6, v100
	v_add_u32_e32 v156, 0xfffffdcf, v100
	v_cndmask_b32_e32 v54, v132, v54, vcc
	v_cmp_lt_u32_e32 vcc, s34, v150
	v_add_u32_e32 v150, 0xfffffdf5, v100
	v_add_u32_e32 v157, 0xfffffdd0, v100
	v_cndmask_b32_e32 v55, v132, v55, vcc
	v_cmp_lt_u32_e32 vcc, s34, v151
	v_add_u32_e32 v151, 0xfffffdf0, v100
	v_add_u32_e32 v158, 0xfffffdd5, v100
	v_cndmask_b32_e32 v56, v132, v56, vcc
	v_cmp_lt_u32_e32 vcc, s34, v150
	v_add_u32_e32 v150, 0xfffffdef, v100
	v_add_u32_e32 v159, 0xfffffdd6, v100
	v_cndmask_b32_e32 v57, v132, v57, vcc
	v_cmp_lt_u32_e32 vcc, s34, v151
	v_add_u32_e32 v151, 0xfffffdee, v100
	v_add_u32_e32 v160, 0xfffffdd7, v100
	v_cndmask_b32_e32 v58, v132, v58, vcc
	v_cmp_lt_u32_e32 vcc, s34, v150
	v_add_u32_e32 v150, 0xfffffded, v100
	v_add_u32_e32 v161, 0xfffffdd8, v100
	v_cndmask_b32_e32 v59, v132, v59, vcc
	v_cmp_lt_u32_e32 vcc, s34, v151
	v_add_u32_e32 v151, 0xfffffde8, v100
	v_add_u32_e32 v162, 0xfffffddd, v100
	v_cndmask_b32_e32 v60, v132, v60, vcc
	v_cmp_lt_u32_e32 vcc, s34, v150
	v_add_u32_e32 v150, 0xfffffde7, v100
	v_add_u32_e32 v163, 0xfffffdde, v100
	v_cndmask_b32_e32 v61, v132, v61, vcc
	v_cmp_lt_u32_e32 vcc, s34, v151
	v_add_u32_e32 v151, 0xfffffde5, v100
	v_add_u32_e32 v164, 0xfffffddf, v100
	v_cndmask_b32_e32 v62, v132, v62, vcc
	v_cmp_lt_u32_e32 vcc, s34, v150
	v_add_u32_e32 v150, 0xfffffde6, v100
	s_nop 0
	v_cndmask_b32_e32 v63, v132, v63, vcc
	v_cmp_lt_u32_e32 vcc, s34, v151
	v_add_u32_e32 v151, 0xfffffdc6, v100
	s_nop 0
	v_cndmask_b32_e32 v65, v132, v65, vcc
	v_cmp_lt_u32_e32 vcc, s34, v150
	v_add_u32_e32 v150, 0xfffffdc5, v100
	v_add_u32_e32 v100, 0xfffffde0, v100
	v_cndmask_b32_e32 v64, v132, v64, vcc
	v_cmp_lt_u32_e32 vcc, s34, v100
	s_nop 1
	v_cndmask_b32_e32 v34, v132, v34, vcc
	v_cmp_lt_u32_e32 vcc, s34, v164
	s_nop 1
	v_cndmask_b32_e32 v35, v132, v35, vcc
	v_cmp_lt_u32_e32 vcc, s34, v163
	s_nop 1
	v_cndmask_b32_e32 v36, v132, v36, vcc
	v_cmp_lt_u32_e32 vcc, s34, v162
	s_nop 1
	v_cndmask_b32_e32 v37, v132, v37, vcc
	v_cmp_lt_u32_e32 vcc, s34, v161
	s_nop 1
	v_cndmask_b32_e32 v38, v132, v38, vcc
	v_cmp_lt_u32_e32 vcc, s34, v160
	s_nop 1
	v_cndmask_b32_e32 v39, v132, v39, vcc
	v_cmp_lt_u32_e32 vcc, s34, v159
	s_nop 1
	v_cndmask_b32_e32 v40, v132, v40, vcc
	v_cmp_lt_u32_e32 vcc, s34, v158
	s_nop 1
	v_cndmask_b32_e32 v41, v132, v41, vcc
	v_cmp_lt_u32_e32 vcc, s34, v157
	s_nop 1
	v_cndmask_b32_e32 v42, v132, v42, vcc
	v_cmp_lt_u32_e32 vcc, s34, v156
	s_nop 1
	v_cndmask_b32_e32 v43, v132, v43, vcc
	v_cmp_lt_u32_e32 vcc, s34, v155
	s_nop 1
	v_cndmask_b32_e32 v44, v132, v44, vcc
	v_cmp_lt_u32_e32 vcc, s34, v154
	s_nop 1
	v_cndmask_b32_e32 v45, v132, v45, vcc
	v_cmp_lt_u32_e32 vcc, s34, v153
	s_nop 1
	v_cndmask_b32_e32 v46, v132, v46, vcc
	v_cmp_lt_u32_e32 vcc, s34, v152
	s_nop 1
	v_cndmask_b32_e32 v47, v132, v47, vcc
	v_cmp_lt_u32_e32 vcc, s34, v151
	s_nop 1
	v_cndmask_b32_e32 v48, v132, v48, vcc
	v_cmp_lt_u32_e32 vcc, s34, v150
	s_nop 1
	v_cndmask_b32_e32 v49, v132, v49, vcc

.LBB0_2884:
	v_exp_f32_e32 v50, v50
	v_exp_f32_e32 v100, v34
	v_exp_f32_e32 v34, v51
	v_exp_f32_e32 v51, v35
	v_exp_f32_e32 v35, v52
	v_exp_f32_e32 v52, v36
	v_exp_f32_e32 v36, v53
	v_exp_f32_e32 v53, v37
	v_exp_f32_e32 v37, v54
	v_exp_f32_e32 v54, v38
	v_exp_f32_e32 v38, v55
	v_exp_f32_e32 v55, v39
	v_exp_f32_e32 v39, v56
	v_exp_f32_e32 v56, v40
	v_exp_f32_e32 v40, v57
	v_exp_f32_e32 v57, v41
	v_exp_f32_e32 v41, v58
	v_exp_f32_e32 v58, v42
	v_exp_f32_e32 v42, v59
	v_exp_f32_e32 v59, v43
	v_exp_f32_e32 v43, v60
	v_exp_f32_e32 v60, v44
	v_exp_f32_e32 v44, v61
	v_exp_f32_e32 v61, v45
	v_exp_f32_e32 v45, v62
	v_exp_f32_e32 v62, v46
	v_exp_f32_e32 v46, v63
	v_exp_f32_e32 v63, v47
	v_exp_f32_e32 v47, v64
	v_exp_f32_e32 v64, v48
	v_exp_f32_e32 v48, v65
	v_exp_f32_e32 v49, v49
	v_cvt_pk_bf16_f32 v150, v50, v34
	v_cvt_pk_bf16_f32 v151, v35, v36
	v_cvt_pk_bf16_f32 v152, v37, v38
	v_cvt_pk_bf16_f32 v153, v39, v40
	v_cvt_pk_bf16_f32 v154, v41, v42
	v_cvt_pk_bf16_f32 v155, v43, v44
	v_cvt_pk_bf16_f32 v156, v45, v46
	v_cvt_pk_bf16_f32 v157, v47, v48
	v_cvt_pk_bf16_f32 v158, v100, v51
	v_cvt_pk_bf16_f32 v159, v52, v53
	v_cvt_pk_bf16_f32 v160, v54, v55
	v_cvt_pk_bf16_f32 v161, v56, v57
	v_cvt_pk_bf16_f32 v162, v58, v59
	v_cvt_pk_bf16_f32 v163, v60, v61
	v_cvt_pk_bf16_f32 v164, v62, v63
	v_cvt_pk_bf16_f32 v165, v64, v49
	v_add_u32_e32 v65, s18, v120
	s_waitcnt lgkmcnt(0)
	s_nop 0
	v_mfma_f32_32x32x16_bf16 v[18:33], v[150:153], v[230:233], v[18:33]
	ds_read_b64_tr_b16 v[168:169],v65 offset:4096
	ds_read_b64_tr_b16 v[170:171],v65 offset:4608
	v_mfma_f32_32x32x16_bf16 v[18:33], v[154:157], v[234:237], v[18:33]
	ds_read_b64_tr_b16 v[172:173],v65 offset:5120
	ds_read_b64_tr_b16 v[174:175],v65 offset:5632
	v_mfma_f32_32x32x16_bf16 v[18:33], v[158:161], v[238:241], v[18:33]
	ds_read_b64_tr_b16 v[176:177],v65 offset:6144
	ds_read_b64_tr_b16 v[178:179],v65 offset:6656
	v_mfma_f32_32x32x16_bf16 v[18:33], v[162:165], v[242:245], v[18:33]
	ds_read_b64_tr_b16 v[180:181],v65 offset:7168
	ds_read_b64_tr_b16 v[182:183],v65 offset:7680
	s_waitcnt lgkmcnt(0)
	v_mfma_f32_32x32x16_bf16 v[2:17], v[150:153], v[168:171], v[2:17]
	s_cmp_ge_u32 s17, s14
	v_mfma_f32_32x32x16_bf16 v[2:17], v[154:157], v[172:175], v[2:17]
	v_mfma_f32_32x32x16_bf16 v[2:17], v[158:161], v[176:179], v[2:17]
	v_mfma_f32_32x32x16_bf16 v[2:17], v[162:165], v[180:183], v[2:17]
	s_cbranch_scc1 .LBB0_2886
	s_xor_b32 s10, s18, 0x2000
	v_add_u32_e32 v65, s10, v119
	s_waitcnt vmcnt(0)
	ds_write_b128 v65, v[82:85]
	ds_write_b128 v65, v[86:89] offset:16384

.LBB0_5386:
	s_and_b32 s43, s31, 0x2000
	v_add_u32_e32 v112, s43, v142
	ds_read_b128 v[34:37], v112
	ds_read_b128 v[146:149], v112 offset:2048
	ds_read_b128 v[230:233], v112 offset:512
	ds_read_b128 v[234:237], v112 offset:2560
	ds_read_b128 v[238:241], v112 offset:4096
	ds_read_b128 v[242:245], v112 offset:4608
	ds_read_b128 v[246:249], v112 offset:6144
	ds_read_b128 v[250:253], v112 offset:6656
	s_waitcnt lgkmcnt(6)
	v_mfma_f32_32x32x16_bf16 v[50:65], v[34:37], v[66:69], 0
	v_mfma_f32_32x32x16_bf16 v[50:65], v[146:149], v[70:73], v[50:65]
	s_waitcnt lgkmcnt(4)
	v_mfma_f32_32x32x16_bf16 v[34:49], v[230:233], v[66:69], 0
	v_mfma_f32_32x32x16_bf16 v[34:49], v[234:237], v[70:73], v[34:49]
	s_waitcnt lgkmcnt(3)
	v_mfma_f32_32x32x16_bf16 v[50:65], v[238:241], v[74:77], v[50:65]
	s_waitcnt lgkmcnt(2)
	v_mfma_f32_32x32x16_bf16 v[34:49], v[242:245], v[74:77], v[34:49]
	s_waitcnt lgkmcnt(1)
	v_mfma_f32_32x32x16_bf16 v[50:65], v[246:249], v[78:81], v[50:65]
	s_waitcnt lgkmcnt(0)
	v_mfma_f32_32x32x16_bf16 v[34:49], v[250:253], v[78:81], v[34:49]
	v_add_u32_e32 v229, s43, v125
	ds_read_b64_tr_b16 v[230:231],v229 offset:0
	ds_read_b64_tr_b16 v[232:233],v229 offset:512
	ds_read_b64_tr_b16 v[234:235],v229 offset:1024
	ds_read_b64_tr_b16 v[236:237],v229 offset:1536
	ds_read_b64_tr_b16 v[238:239],v229 offset:2048
	ds_read_b64_tr_b16 v[240:241],v229 offset:2560
	ds_read_b64_tr_b16 v[242:243],v229 offset:3072
	ds_read_b64_tr_b16 v[244:245],v229 offset:3584
	v_cvt_f32_i32_e32 v112, v121
	v_cmp_lt_i32_e64 s[22:23], 62, v1
	s_cmp_eq_u64 s[22:23], exec
	v_fma_f32 v154, v90, v112, v141
	v_add_f32_e32 v146, v120, v154
	v_add_f32_e32 v148, v105, v154
	v_add_f32_e32 v147, v92, v146
	v_add_f32_e32 v149, v92, v148
	s_nop 0
	v_pk_add_f32 v[112:113], v[146:147], v[50:51]
	v_pk_add_f32 v[50:51], v[102:103], v[146:147] op_sel_hi:[1,0]
	v_add_f32_e32 v152, v107, v154
	v_pk_add_f32 v[50:51], v[50:51], v[52:53]
	v_pk_add_f32 v[52:53], v[148:149], v[54:55]
	v_pk_add_f32 v[54:55], v[102:103], v[148:149] op_sel_hi:[1,0]
	v_add_f32_e32 v149, v119, v154
	v_pk_add_f32 v[54:55], v[54:55], v[56:57]
	v_add_f32_e32 v56, v120, v149
	v_add_f32_e32 v57, v92, v56
	v_pk_add_f32 v[34:35], v[56:57], v[34:35]
	v_add_f32_e32 v57, v102, v56
	v_add_f32_e32 v146, v57, v36
	v_mov_b32_e32 v57, v149
	v_pk_add_f32 v[150:151], v[104:105], v[56:57]
	v_mov_b32_e32 v36, v37
	v_mov_b32_e32 v37, v38
	v_pk_add_f32 v[56:57], v[92:93], v[150:151] op_sel:[0,1]
	v_mov_b32_e32 v38, v39
	v_mov_b32_e32 v39, v40
	v_add_f32_e32 v153, v92, v152
	v_mov_b32_e32 v148, v151
	v_pk_add_f32 v[36:37], v[150:151], v[36:37]
	v_pk_add_f32 v[38:39], v[56:57], v[38:39]
	v_pk_add_f32 v[56:57], v[152:153], v[58:59]
	v_pk_add_f32 v[58:59], v[102:103], v[152:153] op_sel_hi:[1,0]
	v_pk_add_f32 v[150:151], v[106:107], v[148:149]
	v_add_f32_e32 v152, v109, v154
	v_pk_add_f32 v[58:59], v[58:59], v[60:61]
	v_mov_b32_e32 v40, v41
	v_mov_b32_e32 v41, v42
	v_pk_add_f32 v[60:61], v[92:93], v[150:151] op_sel:[0,1]
	v_mov_b32_e32 v42, v43
	v_mov_b32_e32 v43, v44
	v_add_f32_e32 v153, v92, v152
	v_pk_add_f32 v[42:43], v[60:61], v[42:43]
	v_pk_add_f32 v[60:61], v[152:153], v[62:63]
	v_pk_add_f32 v[62:63], v[102:103], v[152:153] op_sel_hi:[1,0]
	v_mov_b32_e32 v148, v151
	v_pk_add_f32 v[62:63], v[62:63], v[64:65]
	v_pk_add_f32 v[64:65], v[108:109], v[148:149]
	v_mov_b32_e32 v44, v45
	v_mov_b32_e32 v45, v46
	v_pk_add_f32 v[148:149], v[92:93], v[64:65] op_sel:[0,1]
	v_mov_b32_e32 v46, v47
	v_mov_b32_e32 v47, v48
	v_add_f32_e32 v48, v104, v65
	v_pk_add_f32 v[40:41], v[150:151], v[40:41]
	v_pk_add_f32 v[44:45], v[64:65], v[44:45]
	v_pk_add_f32 v[46:47], v[148:149], v[46:47]
	v_add_f32_e32 v64, v48, v49
	s_cbranch_scc1 .LBB0_5388
	v_add_u32_e32 v48, v145, v1
	v_cmp_gt_i32_e64 s[22:23], 0, v48
	s_or_b64 s[22:23], s[6:7], s[22:23]
	v_cmp_gt_i32_e64 s[24:25], 40, v48
	v_cndmask_b32_e64 v112, v112, v132, s[22:23]
	v_cmp_gt_i32_e64 s[22:23], 32, v48
	s_or_b64 s[22:23], s[12:13], s[22:23]
	s_nop 0
	v_cndmask_b32_e64 v34, v34, v132, s[22:23]
	v_cmp_gt_i32_e64 s[22:23], 1, v48
	s_or_b64 s[22:23], s[6:7], s[22:23]
	s_nop 0
	v_cndmask_b32_e64 v113, v113, v132, s[22:23]
	v_cmp_gt_i32_e64 s[22:23], 33, v48
	s_or_b64 s[22:23], s[12:13], s[22:23]
	s_nop 0
	v_cndmask_b32_e64 v35, v35, v132, s[22:23]
	v_cmp_gt_i32_e64 s[22:23], 2, v48
	s_or_b64 s[22:23], s[6:7], s[22:23]
	s_nop 0
	v_cndmask_b32_e64 v50, v50, v132, s[22:23]
	v_cmp_gt_i32_e64 s[22:23], 34, v48
	s_or_b64 s[22:23], s[12:13], s[22:23]
	s_nop 0
	v_cndmask_b32_e64 v146, v146, v132, s[22:23]
	v_cmp_gt_i32_e64 s[22:23], 3, v48
	s_or_b64 s[22:23], s[6:7], s[22:23]
	s_nop 0
	v_cndmask_b32_e64 v51, v51, v132, s[22:23]
	v_cmp_gt_i32_e64 s[22:23], 8, v48
	s_or_b64 s[22:23], s[8:9], s[22:23]
	s_nop 0
	v_cndmask_b32_e64 v52, v52, v132, s[22:23]
	v_cmp_gt_i32_e64 s[22:23], 35, v48
	s_or_b64 s[22:23], s[12:13], s[22:23]
	s_nop 0
	v_cndmask_b32_e64 v36, v36, v132, s[22:23]
	s_or_b64 s[22:23], s[10:11], s[24:25]
	v_cndmask_b32_e64 v37, v37, v132, s[22:23]
	v_cmp_gt_i32_e64 s[22:23], 9, v48
	s_or_b64 s[22:23], s[8:9], s[22:23]
	s_nop 0
	v_cndmask_b32_e64 v53, v53, v132, s[22:23]
	v_cmp_gt_i32_e64 s[22:23], 41, v48
	s_or_b64 s[22:23], s[10:11], s[22:23]
	s_nop 0
	v_cndmask_b32_e64 v38, v38, v132, s[22:23]
	v_cmp_gt_i32_e64 s[22:23], 10, v48
	s_or_b64 s[22:23], s[8:9], s[22:23]
	s_nop 0
	v_cndmask_b32_e64 v54, v54, v132, s[22:23]
	v_cmp_gt_i32_e64 s[22:23], 42, v48
	s_or_b64 s[22:23], s[10:11], s[22:23]
	s_nop 0
	v_cndmask_b32_e64 v39, v39, v132, s[22:23]
	v_cmp_gt_i32_e64 s[22:23], 11, v48
	s_or_b64 s[22:23], s[8:9], s[22:23]
	s_nop 0
	v_cndmask_b32_e64 v55, v55, v132, s[22:23]
	v_cmp_gt_i32_e64 s[22:23], 43, v48
	s_or_b64 s[22:23], s[10:11], s[22:23]
	s_nop 0
	v_cndmask_b32_e64 v40, v40, v132, s[22:23]
	v_cmp_gt_i32_e64 s[22:23], 16, v48
	s_or_b64 s[22:23], s[14:15], s[22:23]
	s_nop 0
	v_cndmask_b32_e64 v56, v56, v132, s[22:23]
	v_cmp_gt_i32_e64 s[22:23], 48, v48
	s_or_b64 s[22:23], s[16:17], s[22:23]
	s_nop 0
	v_cndmask_b32_e64 v41, v41, v132, s[22:23]
	v_cmp_gt_i32_e64 s[22:23], 17, v48
	s_or_b64 s[22:23], s[14:15], s[22:23]
	s_nop 0
	v_cndmask_b32_e64 v57, v57, v132, s[22:23]
	v_cmp_gt_i32_e64 s[22:23], 49, v48
	s_or_b64 s[22:23], s[16:17], s[22:23]
	s_nop 0
	v_cndmask_b32_e64 v42, v42, v132, s[22:23]
	v_cmp_gt_i32_e64 s[22:23], 18, v48
	s_or_b64 s[22:23], s[14:15], s[22:23]
	s_nop 0
	v_cndmask_b32_e64 v58, v58, v132, s[22:23]
	v_cmp_gt_i32_e64 s[22:23], 50, v48
	s_or_b64 s[22:23], s[16:17], s[22:23]
	s_nop 0
	v_cndmask_b32_e64 v43, v43, v132, s[22:23]
	v_cmp_gt_i32_e64 s[22:23], 19, v48
	s_or_b64 s[22:23], s[14:15], s[22:23]
	s_nop 0
	v_cndmask_b32_e64 v59, v59, v132, s[22:23]
	v_cmp_gt_i32_e64 s[22:23], 51, v48
	s_or_b64 s[22:23], s[16:17], s[22:23]
	s_nop 0
	v_cndmask_b32_e64 v44, v44, v132, s[22:23]
	v_cmp_gt_i32_e64 s[22:23], 24, v48
	s_or_b64 s[22:23], s[18:19], s[22:23]
	s_nop 0
	v_cndmask_b32_e64 v60, v60, v132, s[22:23]
	v_cmp_gt_i32_e64 s[22:23], 56, v48
	s_or_b64 s[22:23], s[20:21], s[22:23]
	s_nop 0
	v_cndmask_b32_e64 v45, v45, v132, s[22:23]
	v_cmp_gt_i32_e64 s[22:23], 25, v48
	s_or_b64 s[22:23], s[18:19], s[22:23]
	s_nop 0
	v_cndmask_b32_e64 v61, v61, v132, s[22:23]
	v_cmp_gt_i32_e64 s[22:23], 57, v48
	s_or_b64 s[22:23], s[20:21], s[22:23]
	s_nop 0
	v_cndmask_b32_e64 v46, v46, v132, s[22:23]
	v_cmp_gt_i32_e64 s[22:23], 26, v48
	s_or_b64 s[22:23], s[18:19], s[22:23]
	s_nop 0
	v_cndmask_b32_e64 v62, v62, v132, s[22:23]
	v_cmp_gt_i32_e64 s[22:23], 58, v48
	s_or_b64 s[22:23], s[20:21], s[22:23]
	s_nop 0
	v_cndmask_b32_e64 v47, v47, v132, s[22:23]
	v_cmp_gt_i32_e64 s[22:23], 27, v48
	s_or_b64 s[22:23], s[18:19], s[22:23]
	s_nop 0
	v_cndmask_b32_e64 v63, v63, v132, s[22:23]
	v_cmp_gt_i32_e64 s[22:23], 59, v48
	s_or_b64 s[22:23], s[20:21], s[22:23]
	s_nop 0
	v_cndmask_b32_e64 v64, v64, v132, s[22:23]

.LBB0_5392:
	s_or_b64 exec, exec, s[22:23]
	v_mul_f32_e32 v45, v123, v65
	s_waitcnt lgkmcnt(0)
	v_mul_f32_e32 v46, v123, v112
	v_mul_f32_e32 v47, v123, v113
	v_mul_f32_e32 v60, v123, v147
	v_mul_f32_e32 v56, v123, v56
	v_mul_f32_e32 v57, v123, v57
	v_mul_f32_e32 v58, v123, v58
	v_mul_f32_e32 v59, v123, v59
	v_mul_f32_e32 v61, v123, v62
	v_mul_f32_e32 v62, v123, v63
	v_mul_f32_e32 v63, v123, v146
	v_mul_f32_e32 v64, v123, v148
	v_mul_f32_e32 v65, v123, v149
	v_mul_f32_e32 v112, v123, v42
	v_mul_f32_e32 v113, v123, v43
	v_mul_f32_e32 v146, v123, v44
	v_cvt_pk_bf16_f32 v42, v45, v55
	v_cvt_pk_bf16_f32 v43, v46, v54
	v_cvt_pk_bf16_f32 v44, v47, v53
	v_cvt_pk_bf16_f32 v45, v60, v52
	v_cvt_pk_bf16_f32 v52, v56, v51
	v_cvt_pk_bf16_f32 v53, v57, v50
	v_cvt_pk_bf16_f32 v54, v58, v49
	v_cvt_pk_bf16_f32 v55, v59, v48
	v_cvt_pk_bf16_f32 v46, v61, v41
	v_cvt_pk_bf16_f32 v47, v62, v40
	v_cvt_pk_bf16_f32 v48, v63, v39
	v_cvt_pk_bf16_f32 v49, v64, v38
	v_cvt_pk_bf16_f32 v38, v65, v37
	v_cvt_pk_bf16_f32 v39, v112, v36
	v_cvt_pk_bf16_f32 v40, v113, v35
	v_cvt_pk_bf16_f32 v41, v146, v34
	v_add_u32_e32 v50, s43, v125
	s_waitcnt lgkmcnt(0)
	s_nop 0
	v_mfma_f32_32x32x16_bf16 v[18:33], v[42:45], v[230:233], v[18:33]
	ds_read_b64_tr_b16 v[34:35],v50 offset:4096
	ds_read_b64_tr_b16 v[36:37],v50 offset:4608
	v_mfma_f32_32x32x16_bf16 v[18:33], v[52:55], v[234:237], v[18:33]
	ds_read_b64_tr_b16 v[56:57],v50 offset:5120
	ds_read_b64_tr_b16 v[58:59],v50 offset:5632
	v_mfma_f32_32x32x16_bf16 v[18:33], v[46:49], v[238:241], v[18:33]
	ds_read_b64_tr_b16 v[60:61],v50 offset:6144
	ds_read_b64_tr_b16 v[62:63],v50 offset:6656
	v_mfma_f32_32x32x16_bf16 v[18:33], v[38:41], v[242:245], v[18:33]
	ds_read_b64_tr_b16 v[146:147],v50 offset:7168
	ds_read_b64_tr_b16 v[148:149],v50 offset:7680
	s_waitcnt lgkmcnt(0)
	v_mfma_f32_32x32x16_bf16 v[2:17], v[42:45], v[34:37], v[2:17]
	s_cmp_ge_u32 s42, s30
	v_mfma_f32_32x32x16_bf16 v[2:17], v[52:55], v[56:59], v[2:17]
	v_mfma_f32_32x32x16_bf16 v[2:17], v[46:49], v[60:63], v[2:17]
	v_mfma_f32_32x32x16_bf16 v[2:17], v[38:41], v[146:149], v[2:17]
	s_cbranch_scc1 .LBB0_5394
	s_xor_b32 s22, s43, 0x2000
	v_add_u32_e32 v34, s22, v124
	s_waitcnt vmcnt(0)
	ds_write_b128 v34, v[82:85]
	ds_write_b128 v34, v[86:89] offset:16384

.LBB0_5427:
	s_add_i32 s26, s28, -8
	v_mov_b32_e32 v34, s26
	ds_read_b32 v116, v34
	s_and_b32 s47, s46, 1
	s_waitcnt lgkmcnt(0)
	v_ashrrev_i32_e32 v34, 5, v116
	v_lshl_add_u32 v98, v34, 2, v165
	ds_read_b32 v34, v98
	v_lshlrev_b32_e64 v109, v116, 1
	s_waitcnt lgkmcnt(0)
	v_and_b32_e32 v34, v109, v34
	v_cmp_ne_u32_e32 vcc, 0, v34
	s_cbranch_vccz .LBB0_5436
	s_lshl_b32 s81, s47, 13
	v_add_u32_e32 v117, s81, v167
	ds_read_b128 v[34:37], v117
	ds_read_b128 v[118:121], v117 offset:2048
	ds_read_b128 v[230:233], v117 offset:512
	ds_read_b128 v[234:237], v117 offset:2560
	ds_read_b128 v[238:241], v117 offset:4096
	ds_read_b128 v[242:245], v117 offset:4608
	ds_read_b128 v[246:249], v117 offset:6144
	ds_read_b128 v[250:253], v117 offset:6656
	s_waitcnt lgkmcnt(6)
	v_mfma_f32_32x32x16_bf16 v[50:65], v[34:37], v[66:69], 0
	v_mfma_f32_32x32x16_bf16 v[50:65], v[118:121], v[70:73], v[50:65]
	s_waitcnt lgkmcnt(4)
	v_mfma_f32_32x32x16_bf16 v[34:49], v[230:233], v[66:69], 0
	v_mfma_f32_32x32x16_bf16 v[34:49], v[234:237], v[70:73], v[34:49]
	s_waitcnt lgkmcnt(3)
	v_mfma_f32_32x32x16_bf16 v[50:65], v[238:241], v[74:77], v[50:65]
	s_waitcnt lgkmcnt(2)
	v_mfma_f32_32x32x16_bf16 v[34:49], v[242:245], v[74:77], v[34:49]
	s_waitcnt lgkmcnt(1)
	v_mfma_f32_32x32x16_bf16 v[50:65], v[246:249], v[78:81], v[50:65]
	s_waitcnt lgkmcnt(0)
	v_mfma_f32_32x32x16_bf16 v[34:49], v[250:253], v[78:81], v[34:49]
	v_add_u32_e32 v229, s81, v163
	ds_read_b64_tr_b16 v[230:231],v229 offset:0
	ds_read_b64_tr_b16 v[232:233],v229 offset:512
	ds_read_b64_tr_b16 v[234:235],v229 offset:1024
	ds_read_b64_tr_b16 v[236:237],v229 offset:1536
	ds_read_b64_tr_b16 v[238:239],v229 offset:2048
	ds_read_b64_tr_b16 v[240:241],v229 offset:2560
	ds_read_b64_tr_b16 v[242:243],v229 offset:3072
	ds_read_b64_tr_b16 v[244:245],v229 offset:3584
	v_lshlrev_b32_e32 v116, 6, v116
	ds_read_b32 v117, v98
	v_sub_u32_e32 v98, v116, v96
	v_cvt_f32_i32_e32 v118, v98
	v_sub_u32_e32 v98, v96, v116
	v_cmp_lt_i32_e32 vcc, 62, v98
	s_waitcnt lgkmcnt(0)
	v_and_b32_e32 v109, v117, v109
	v_fma_f32 v116, v90, v118, v164
	v_sub_f32_e32 v171, v116, v168
	v_add_f32_e32 v116, v144, v171
	v_add_f32_e32 v117, v90, v116
	v_pk_add_f32 v[118:119], v[116:117], v[50:51]
	v_pk_add_f32 v[50:51], v[114:115], v[116:117] op_sel_hi:[1,0]
	v_add_f32_e32 v173, v143, v171
	v_pk_add_f32 v[116:117], v[50:51], v[52:53]
	v_add_f32_e32 v50, v111, v171
	v_add_f32_e32 v51, v90, v50
	v_add_f32_e32 v120, v144, v173
	v_pk_add_f32 v[52:53], v[50:51], v[54:55]
	v_pk_add_f32 v[50:51], v[114:115], v[50:51] op_sel_hi:[1,0]
	v_add_f32_e32 v121, v90, v120
	v_pk_add_f32 v[50:51], v[50:51], v[56:57]
	v_pk_add_f32 v[56:57], v[120:121], v[34:35]
	v_add_f32_e32 v34, v91, v120
	v_mov_b32_e32 v121, v173
	v_add_f32_e32 v54, v34, v36
	v_pk_add_f32 v[122:123], v[110:111], v[120:121]
	v_mov_b32_e32 v34, v37
	v_mov_b32_e32 v35, v38
	v_pk_add_f32 v[124:125], v[122:123], v[34:35]
	v_pk_add_f32 v[34:35], v[90:91], v[122:123] op_sel:[0,1]
	v_mov_b32_e32 v36, v39
	v_mov_b32_e32 v37, v40
	v_pk_add_f32 v[120:121], v[34:35], v[36:37]
	v_add_f32_e32 v34, v92, v171
	v_add_f32_e32 v35, v90, v34
	v_pk_add_f32 v[38:39], v[34:35], v[58:59]
	v_pk_add_f32 v[34:35], v[114:115], v[34:35] op_sel_hi:[1,0]
	v_mov_b32_e32 v172, v123
	v_pk_add_f32 v[34:35], v[34:35], v[60:61]
	v_pk_add_f32 v[60:61], v[112:113], v[172:173]
	v_mov_b32_e32 v36, v41
	v_mov_b32_e32 v37, v42
	v_pk_add_f32 v[122:123], v[60:61], v[36:37]
	v_pk_add_f32 v[36:37], v[90:91], v[60:61] op_sel:[0,1]
	v_mov_b32_e32 v40, v43
	v_mov_b32_e32 v41, v44
	v_mov_b32_e32 v172, v61
	v_cmp_ne_u32_e64 s[26:27], 0, v109
	v_pk_add_f32 v[58:59], v[36:37], v[40:41]
	v_add_f32_e32 v36, v103, v171
	v_pk_add_f32 v[42:43], v[102:103], v[172:173]
	v_mov_b32_e32 v44, v45
	v_mov_b32_e32 v45, v46
	s_and_b64 vcc, s[26:27], vcc
	v_add_f32_e32 v37, v90, v36
	v_pk_add_f32 v[60:61], v[42:43], v[44:45]
	v_pk_add_f32 v[44:45], v[90:91], v[42:43] op_sel:[0,1]
	v_add_f32_e32 v42, v110, v43
	v_pk_add_f32 v[40:41], v[36:37], v[62:63]
	v_pk_add_f32 v[36:37], v[114:115], v[36:37] op_sel_hi:[1,0]
	v_mov_b32_e32 v46, v47
	v_mov_b32_e32 v47, v48
	v_pk_add_f32 v[36:37], v[36:37], v[64:65]
	v_pk_add_f32 v[62:63], v[44:45], v[46:47]
	s_cmp_eq_u64 vcc, exec
	v_add_f32_e32 v43, v42, v49
	s_cbranch_scc1 .LBB0_5430
	v_sub_u32_e32 v42, v98, v162
	v_cndmask_b32_e64 v64, v134, v42, s[26:27]
	v_cmp_gt_i32_e32 vcc, 0, v64
	s_or_b64 vcc, s[10:11], vcc
	v_cmp_gt_i32_e64 s[26:27], 40, v64
	v_cndmask_b32_e32 v118, v118, v132, vcc
	v_cmp_gt_i32_e32 vcc, 32, v64
	s_or_b64 vcc, s[16:17], vcc
	s_nop 0
	v_cndmask_b32_e32 v56, v56, v132, vcc
	v_cmp_gt_i32_e32 vcc, 1, v64
	s_or_b64 vcc, s[10:11], vcc
	s_nop 0
	v_cndmask_b32_e32 v119, v119, v132, vcc
	v_cmp_gt_i32_e32 vcc, 33, v64
	s_or_b64 vcc, s[16:17], vcc
	s_nop 0
	v_cndmask_b32_e32 v57, v57, v132, vcc
	v_cmp_gt_i32_e32 vcc, 2, v64
	s_or_b64 vcc, s[10:11], vcc
	s_nop 0
	v_cndmask_b32_e32 v116, v116, v132, vcc
	v_cmp_gt_i32_e32 vcc, 34, v64
	s_or_b64 vcc, s[16:17], vcc
	s_nop 0
	v_cndmask_b32_e32 v54, v54, v132, vcc
	v_cmp_gt_i32_e32 vcc, 3, v64
	s_or_b64 vcc, s[10:11], vcc
	s_nop 0
	v_cndmask_b32_e32 v117, v117, v132, vcc
	v_cmp_gt_i32_e32 vcc, 8, v64
	s_or_b64 vcc, s[12:13], vcc
	s_nop 0
	v_cndmask_b32_e32 v52, v52, v132, vcc
	v_cmp_gt_i32_e32 vcc, 35, v64
	s_or_b64 vcc, s[16:17], vcc
	s_nop 0
	v_cndmask_b32_e32 v55, v124, v132, vcc
	s_or_b64 vcc, s[14:15], s[26:27]
	v_cndmask_b32_e32 v44, v125, v132, vcc
	v_cmp_gt_i32_e32 vcc, 9, v64
	s_or_b64 vcc, s[12:13], vcc
	s_nop 0
	v_cndmask_b32_e32 v53, v53, v132, vcc
	v_cmp_gt_i32_e32 vcc, 41, v64
	s_or_b64 vcc, s[14:15], vcc
	s_nop 0
	v_cndmask_b32_e32 v45, v120, v132, vcc
	v_cmp_gt_i32_e32 vcc, 10, v64
	s_or_b64 vcc, s[12:13], vcc
	s_nop 0
	v_cndmask_b32_e32 v50, v50, v132, vcc
	v_cmp_gt_i32_e32 vcc, 42, v64
	s_or_b64 vcc, s[14:15], vcc
	s_nop 0
	v_cndmask_b32_e32 v46, v121, v132, vcc
	v_cmp_gt_i32_e32 vcc, 11, v64
	s_or_b64 vcc, s[12:13], vcc
	s_nop 0
	v_cndmask_b32_e32 v51, v51, v132, vcc
	v_cmp_gt_i32_e32 vcc, 43, v64
	s_or_b64 vcc, s[14:15], vcc
	s_nop 0
	v_cndmask_b32_e32 v47, v122, v132, vcc
	v_cmp_gt_i32_e32 vcc, 16, v64
	s_or_b64 vcc, s[18:19], vcc
	s_nop 0
	v_cndmask_b32_e32 v38, v38, v132, vcc
	v_cmp_gt_i32_e32 vcc, 48, v64
	s_or_b64 vcc, s[20:21], vcc
	s_nop 0
	v_cndmask_b32_e32 v48, v123, v132, vcc
	v_cmp_gt_i32_e32 vcc, 17, v64
	s_or_b64 vcc, s[18:19], vcc
	s_nop 0
	v_cndmask_b32_e32 v39, v39, v132, vcc
	v_cmp_gt_i32_e32 vcc, 49, v64
	s_or_b64 vcc, s[20:21], vcc
	s_nop 0
	v_cndmask_b32_e32 v49, v58, v132, vcc
	v_cmp_gt_i32_e32 vcc, 18, v64
	s_or_b64 vcc, s[18:19], vcc
	s_nop 0
	v_cndmask_b32_e32 v34, v34, v132, vcc
	v_cmp_gt_i32_e32 vcc, 50, v64
	s_or_b64 vcc, s[20:21], vcc
	s_nop 0
	v_cndmask_b32_e32 v58, v59, v132, vcc
	v_cmp_gt_i32_e32 vcc, 19, v64
	s_or_b64 vcc, s[18:19], vcc
	s_nop 0
	v_cndmask_b32_e32 v35, v35, v132, vcc
	v_cmp_gt_i32_e32 vcc, 51, v64
	s_or_b64 vcc, s[20:21], vcc
	s_nop 0
	v_cndmask_b32_e32 v59, v60, v132, vcc
	v_cmp_gt_i32_e32 vcc, 24, v64
	s_or_b64 vcc, s[22:23], vcc
	s_nop 0
	v_cndmask_b32_e32 v40, v40, v132, vcc
	v_cmp_gt_i32_e32 vcc, 56, v64
	s_or_b64 vcc, s[24:25], vcc
	s_nop 0
	v_cndmask_b32_e32 v60, v61, v132, vcc
	v_cmp_gt_i32_e32 vcc, 25, v64
	s_or_b64 vcc, s[22:23], vcc
	s_nop 0
	v_cndmask_b32_e32 v41, v41, v132, vcc
	v_cmp_gt_i32_e32 vcc, 57, v64
	s_or_b64 vcc, s[24:25], vcc
	s_nop 0
	v_cndmask_b32_e32 v61, v62, v132, vcc
	v_cmp_gt_i32_e32 vcc, 26, v64
	s_or_b64 vcc, s[22:23], vcc
	s_nop 0
	v_cndmask_b32_e32 v36, v36, v132, vcc
	v_cmp_gt_i32_e32 vcc, 58, v64
	s_or_b64 vcc, s[24:25], vcc
	s_nop 0
	v_cndmask_b32_e32 v42, v63, v132, vcc
	v_cmp_gt_i32_e32 vcc, 27, v64
	s_or_b64 vcc, s[22:23], vcc
	s_nop 0
	v_cndmask_b32_e32 v37, v37, v132, vcc
	v_cmp_gt_i32_e32 vcc, 59, v64
	s_or_b64 vcc, s[24:25], vcc
	s_nop 0
	v_cndmask_b32_e32 v43, v43, v132, vcc
	s_branch .LBB0_5431

.LBB0_5435:
	v_exp_f32_e32 v109, v118
	v_exp_f32_e32 v124, v56
	v_exp_f32_e32 v98, v119
	v_exp_f32_e32 v56, v57
	v_exp_f32_e32 v125, v54
	v_add_f32_e32 v57, v109, v124
	v_exp_f32_e32 v54, v55
	v_pk_add_f32 v[62:63], v[56:57], v[98:99]
	v_exp_f32_e32 v57, v116
	v_pk_add_f32 v[62:63], v[62:63], v[62:63] op_sel_hi:[0,1]
	v_exp_f32_e32 v62, v117
	v_exp_f32_e32 v40, v40
	v_add_f32_e32 v55, v125, v57
	v_exp_f32_e32 v122, v43
	v_pk_add_f32 v[64:65], v[54:55], v[62:63]
	v_exp_f32_e32 v55, v52
	v_pk_add_f32 v[64:65], v[64:65], v[64:65] op_sel_hi:[0,1]
	v_exp_f32_e32 v63, v44
	v_exp_f32_e32 v64, v53
	v_exp_f32_e32 v44, v45
	v_add_f32_e32 v45, v63, v55
	v_pk_add_f32 v[52:53], v[44:45], v[64:65]
	s_nop 0
	v_pk_add_f32 v[52:53], v[52:53], v[52:53] op_sel_hi:[0,1]
	v_exp_f32_e32 v45, v50
	v_exp_f32_e32 v65, v46
	v_exp_f32_e32 v52, v51
	v_exp_f32_e32 v46, v47
	v_add_f32_e32 v47, v65, v45
	v_pk_add_f32 v[50:51], v[46:47], v[52:53]
	s_nop 0
	v_pk_add_f32 v[50:51], v[50:51], v[50:51] op_sel_hi:[0,1]
	v_exp_f32_e32 v47, v38
	v_exp_f32_e32 v53, v48
	v_exp_f32_e32 v50, v39
	v_exp_f32_e32 v48, v49
	v_add_f32_e32 v49, v53, v47
	v_pk_add_f32 v[38:39], v[48:49], v[50:51]
	s_nop 0
	v_pk_add_f32 v[116:117], v[38:39], v[38:39] op_sel_hi:[0,1]
	v_exp_f32_e32 v39, v34
	v_exp_f32_e32 v49, v58
	v_exp_f32_e32 v116, v35
	v_exp_f32_e32 v58, v59
	v_exp_f32_e32 v51, v60
	v_add_f32_e32 v59, v49, v39
	v_exp_f32_e32 v60, v61
	v_pk_add_f32 v[34:35], v[58:59], v[116:117]
	v_add_f32_e32 v61, v51, v40
	v_pk_add_f32 v[118:119], v[34:35], v[34:35] op_sel_hi:[0,1]
	v_exp_f32_e32 v118, v41
	v_exp_f32_e32 v41, v36
	v_exp_f32_e32 v59, v42
	v_pk_add_f32 v[34:35], v[60:61], v[118:119]
	s_nop 0
	v_pk_add_f32 v[120:121], v[34:35], v[34:35] op_sel_hi:[0,1]
	v_exp_f32_e32 v120, v37
	v_add_f32_e32 v123, v59, v41
	v_pk_add_f32 v[34:35], v[122:123], v[120:121]
	s_nop 0
	v_add_f32_e32 v34, v34, v35
	v_add_f32_e32 v160, v160, v34
	v_cvt_pk_bf16_f32 v34, v109, v98
	v_cvt_pk_bf16_f32 v35, v57, v62
	v_cvt_pk_bf16_f32 v36, v55, v64
	v_cvt_pk_bf16_f32 v37, v45, v52
	v_cvt_pk_bf16_f32 v38, v47, v50
	v_cvt_pk_bf16_f32 v39, v39, v116
	v_cvt_pk_bf16_f32 v40, v40, v118
	v_cvt_pk_bf16_f32 v41, v41, v120
	v_cvt_pk_bf16_f32 v42, v124, v56
	v_cvt_pk_bf16_f32 v43, v125, v54
	v_cvt_pk_bf16_f32 v44, v63, v44
	v_cvt_pk_bf16_f32 v45, v65, v46
	v_cvt_pk_bf16_f32 v46, v53, v48
	v_cvt_pk_bf16_f32 v47, v49, v58
	v_cvt_pk_bf16_f32 v48, v51, v60
	v_cvt_pk_bf16_f32 v49, v59, v122
	v_add_u32_e32 v98, s81, v163
	s_waitcnt lgkmcnt(0)
	s_nop 0
	v_mfma_f32_32x32x16_bf16 v[18:33], v[34:37], v[230:233], v[18:33]
	ds_read_b64_tr_b16 v[50:51],v98 offset:4096
	ds_read_b64_tr_b16 v[52:53],v98 offset:4608
	v_mfma_f32_32x32x16_bf16 v[18:33], v[38:41], v[234:237], v[18:33]
	ds_read_b64_tr_b16 v[54:55],v98 offset:5120
	ds_read_b64_tr_b16 v[56:57],v98 offset:5632
	v_mfma_f32_32x32x16_bf16 v[18:33], v[42:45], v[238:241], v[18:33]
	ds_read_b64_tr_b16 v[58:59],v98 offset:6144
	ds_read_b64_tr_b16 v[60:61],v98 offset:6656
	v_mfma_f32_32x32x16_bf16 v[18:33], v[46:49], v[242:245], v[18:33]
	ds_read_b64_tr_b16 v[62:63],v98 offset:7168
	ds_read_b64_tr_b16 v[64:65],v98 offset:7680
	s_waitcnt lgkmcnt(0)
	v_mfma_f32_32x32x16_bf16 v[2:17], v[34:37], v[50:53], v[2:17]
	v_mfma_f32_32x32x16_bf16 v[2:17], v[38:41], v[54:57], v[2:17]
	v_mfma_f32_32x32x16_bf16 v[2:17], v[42:45], v[58:61], v[2:17]
	v_mfma_f32_32x32x16_bf16 v[2:17], v[46:49], v[62:65], v[2:17]
